# rw_scan step waves run at s_setprio 2 (conversion waves stay at 0)
# speedup vs baseline: 1.0768x; 1.0031x over previous
; #define LAS __attribute__((address_space(3)))
; __device__ __forceinline__ void phase_rw_scan(KP P, const Ctx& c) {
;     const bf16_t* R = (const bf16_t*)(P->ws + L_RKV); const bf16_t* Kx = R + TD; const bf16_t* Vx = R + 2 * TD;
;     const bf16_t* W = (const bf16_t*)(P->ws + L_W); const bf16_t* AD = (const bf16_t*)(P->ws + L_AD);
;     LAS float* rL = (LAS float*)c.lds; LAS float* wL = rL + 4096; LAS float* kkL = rL + 8192; LAS float* bL = rL + 12288; LAS float* kdL = rL + 16384; LAS float* vL = rL + 20480; LAS float* yL = rL + 24576; LAS float* scL = rL + 28672;
;     const int tok = c.tid >> 3, cq = c.tid & 7;
;     for (int chain = blockIdx.x; chain < 256; chain += gridDim.x) {
;         const int b = chain >> 6, hd = (chain >> 1) & 31, dir = chain & 1;
;         bf16_t* Y = (bf16_t*)(P->ws + (dir ? L_Y1 : L_Y0));
;         const int ch0 = hd * 64 + cq * 8;
;         float kkw[8], kaw[8];
; #pragma unroll
;         for (int j = 0; j < 8; ++j) { kkw[j] = P->in[I_RWKK][ch0 + j]; kaw[j] = P->in[I_RWKA][ch0 + j]; }
;         float s[8] = {0.f, 0.f, 0.f, 0.f, 0.f, 0.f, 0.f, 0.f};
;         u32x4 gr, gk, gv, gw, ga;
;     ...
;         RW_GLOAD(0);
;         for (int ck = 0; ck < SLEN / 64; ++ck) {
;             const int row = seq_row(b, dir, ck * 64 + tok);
;             float r8[8], k8[8], v8[8], w8[8], a8[8];
;             unpack8(gr, r8); unpack8(gk, k8); unpack8(gv, v8); unpack8(gw, w8); unpack8(ga, a8);
;             float kx[8], ss = 0.f;
; #pragma unroll
;             for (int j = 0; j < 8; ++j) { kx[j] = k8[j] * kkw[j]; ss += kx[j] * kx[j]; }
;             ss = sum8(ss);
;             const float rn = rsqrtf(ss + 1e-12f);
;             __syncthreads();
;             float pbr = 0.f, pkr = 0.f;
;             {   float wr_[8], kk_[8], b_[8], kd_[8];
; #pragma unroll
;                 for (int j = 0; j < 8; ++j) { kk_[j] = kx[j] * rn; b_[j] = kk_[j] * a8[j]; kd_[j] = k8[j] * (1.0f + (a8[j] - 1.0f) * kaw[j]); wr_[j] = w8[j] * r8[j]; pbr += b_[j] * r8[j]; pkr += kd_[j] * r8[j]; }
;                 const int o = tok * 64 + cq * 8;
; #pragma unroll
;                 for (int hh = 0; hh < 2; ++hh) { const int q = 4 * hh;
;                     *(LAS f32x4*)(rL + o + q) = (f32x4){wr_[q], wr_[q + 1], wr_[q + 2], wr_[q + 3]}; *(LAS f32x4*)(wL + o + q) = (f32x4){w8[q], w8[q + 1], w8[q + 2], w8[q + 3]};
.LBB0_1759:
	v_readfirstlane_b32 s63, v0
	v_and_b32_e32 v240, 7, v0
	v_lshrrev_b32_e32 v242, 3, v0
	s_cmpk_ge_u32 s63, 0x100
	s_cbranch_scc1 .Lrw_cv
	v_cmp_eq_u32_e64 s[60:61], 0, v240
	v_lshlrev_b32_e32 v240, 5, v240
	v_lshlrev_b32_e32 v242, 3, v242
	v_add_u32_e32 v241, 0x10000, v240
	v_add_u32_e32 v242, 0x14000, v242
	v_mov_b32_e32 v243, 0x1c000
	s_mov_b32 s62, 0
	ds_read_b128 v[38:41], v240 offset:32768
	ds_read_b128 v[42:45], v240 offset:32784
	ds_read_b128 v[46:49], v240 offset:0
	ds_read_b128 v[50:53], v240 offset:16
	ds_read_b128 v[54:57], v240 offset:16384
	ds_read_b128 v[58:61], v240 offset:16400
	ds_read_b128 v[62:65], v241 offset:0
	ds_read_b128 v[66:69], v241 offset:16
	ds_read_b64 v[78:79], v242 offset:0
	ds_read_b128 v[70:73], v240 offset:49152
	ds_read_b128 v[74:77], v240 offset:49168
	ds_read_b64 v[80:81], v243 offset:0
	ds_read_b32 v245, v243
	s_setprio 2
.Lrw_loop:
	s_waitcnt lgkmcnt(9)
	v_pk_mul_f32 v[230:231], v[170:171], v[38:39] op_sel_hi:[1,0]
	v_pk_mul_f32 v[232:233], v[170:171], v[46:47] op_sel_hi:[1,0]
	v_pk_fma_f32 v[230:231], v[172:173], v[38:39], v[230:231] op_sel:[0,1,0]
	v_pk_fma_f32 v[232:233], v[172:173], v[46:47], v[232:233] op_sel:[0,1,0]
	v_pk_fma_f32 v[230:231], v[174:175], v[40:41], v[230:231] op_sel_hi:[1,0,1]
	v_pk_fma_f32 v[232:233], v[174:175], v[48:49], v[232:233] op_sel_hi:[1,0,1]
	v_pk_fma_f32 v[230:231], v[176:177], v[40:41], v[230:231] op_sel:[0,1,0]
	v_pk_fma_f32 v[232:233], v[176:177], v[48:49], v[232:233] op_sel:[0,1,0]
	v_pk_fma_f32 v[230:231], v[178:179], v[42:43], v[230:231] op_sel_hi:[1,0,1]
	v_pk_fma_f32 v[232:233], v[178:179], v[50:51], v[232:233] op_sel_hi:[1,0,1]
	v_pk_fma_f32 v[230:231], v[180:181], v[42:43], v[230:231] op_sel:[0,1,0]
	v_pk_fma_f32 v[232:233], v[180:181], v[50:51], v[232:233] op_sel:[0,1,0]
	v_pk_fma_f32 v[230:231], v[182:183], v[44:45], v[230:231] op_sel_hi:[1,0,1]
	v_pk_fma_f32 v[232:233], v[182:183], v[52:53], v[232:233] op_sel_hi:[1,0,1]
	v_pk_fma_f32 v[230:231], v[184:185], v[44:45], v[230:231] op_sel:[0,1,0]
	v_pk_fma_f32 v[232:233], v[184:185], v[52:53], v[232:233] op_sel:[0,1,0]
	ds_read_b128 v[186:189], v240 offset:33024
	ds_read_b128 v[190:193], v240 offset:33040
	ds_read_b128 v[194:197], v240 offset:256
	ds_read_b128 v[198:201], v240 offset:272
	s_waitcnt lgkmcnt(8)
	v_pk_mul_f32 v[82:83], v[170:171], v[54:55] op_sel_hi:[1,0]
	v_pk_mul_f32 v[84:85], v[172:173], v[54:55] op_sel:[0,1]
	v_pk_mul_f32 v[86:87], v[174:175], v[56:57] op_sel_hi:[1,0]
	v_pk_mul_f32 v[88:89], v[176:177], v[56:57] op_sel:[0,1]
	v_add_f32_dpp v230, v230, v230 quad_perm:[1,0,3,2] row_mask:0xf bank_mask:0xf
	v_pk_mul_f32 v[90:91], v[178:179], v[58:59] op_sel_hi:[1,0]
	v_add_f32_dpp v231, v231, v231 quad_perm:[1,0,3,2] row_mask:0xf bank_mask:0xf
	v_pk_mul_f32 v[92:93], v[180:181], v[58:59] op_sel:[0,1]
	v_add_f32_dpp v232, v232, v232 quad_perm:[1,0,3,2] row_mask:0xf bank_mask:0xf
	v_pk_mul_f32 v[94:95], v[182:183], v[60:61] op_sel_hi:[1,0]
	v_add_f32_dpp v233, v233, v233 quad_perm:[1,0,3,2] row_mask:0xf bank_mask:0xf
	v_pk_mul_f32 v[96:97], v[184:185], v[60:61] op_sel:[0,1]
	v_add_f32_dpp v230, v230, v230 quad_perm:[2,3,0,1] row_mask:0xf bank_mask:0xf
	v_pk_fma_f32 v[82:83], v[78:79], v[62:63], v[82:83] op_sel_hi:[1,0,1]
	v_add_f32_dpp v231, v231, v231 quad_perm:[2,3,0,1] row_mask:0xf bank_mask:0xf
	v_pk_fma_f32 v[84:85], v[78:79], v[62:63], v[84:85] op_sel:[0,1,0]
	v_add_f32_dpp v232, v232, v232 quad_perm:[2,3,0,1] row_mask:0xf bank_mask:0xf
	v_pk_fma_f32 v[86:87], v[78:79], v[64:65], v[86:87] op_sel_hi:[1,0,1]
	v_add_f32_dpp v233, v233, v233 quad_perm:[2,3,0,1] row_mask:0xf bank_mask:0xf
	v_pk_fma_f32 v[88:89], v[78:79], v[64:65], v[88:89] op_sel:[0,1,0]
	v_add_f32_dpp v230, v230, v230 row_half_mirror row_mask:0xf bank_mask:0xf
	v_pk_fma_f32 v[90:91], v[78:79], v[66:67], v[90:91] op_sel_hi:[1,0,1]
	v_add_f32_dpp v231, v231, v231 row_half_mirror row_mask:0xf bank_mask:0xf
	v_pk_fma_f32 v[92:93], v[78:79], v[66:67], v[92:93] op_sel:[0,1,0]
	v_add_f32_dpp v232, v232, v232 row_half_mirror row_mask:0xf bank_mask:0xf
	v_pk_fma_f32 v[94:95], v[78:79], v[68:69], v[94:95] op_sel_hi:[1,0,1]
	v_add_f32_dpp v233, v233, v233 row_half_mirror row_mask:0xf bank_mask:0xf
	v_pk_fma_f32 v[96:97], v[78:79], v[68:69], v[96:97] op_sel:[0,1,0]
	ds_read_b128 v[202:205], v240 offset:16640
	ds_read_b128 v[206:209], v240 offset:16656
	ds_read_b128 v[210:213], v241 offset:256
	ds_read_b128 v[214:217], v241 offset:272
	ds_read_b64 v[226:227], v242 offset:256
	s_waitcnt lgkmcnt(10)
	v_pk_fma_f32 v[234:235], v[230:231], v[80:81], v[232:233] op_sel_hi:[1,0,1] neg_lo:[1,0,0] neg_hi:[1,0,0]
	v_pk_fma_f32 v[170:171], v[230:231], v[70:71], v[82:83] op_sel_hi:[1,0,1] neg_lo:[1,0,0] neg_hi:[1,0,0]
	v_pk_fma_f32 v[172:173], v[230:231], v[70:71], v[84:85] op_sel:[0,1,0] neg_lo:[1,0,0] neg_hi:[1,0,0]
	v_pk_fma_f32 v[174:175], v[230:231], v[72:73], v[86:87] op_sel_hi:[1,0,1] neg_lo:[1,0,0] neg_hi:[1,0,0]
	v_pk_fma_f32 v[176:177], v[230:231], v[72:73], v[88:89] op_sel:[0,1,0] neg_lo:[1,0,0] neg_hi:[1,0,0]
	v_pk_fma_f32 v[178:179], v[230:231], v[74:75], v[90:91] op_sel_hi:[1,0,1] neg_lo:[1,0,0] neg_hi:[1,0,0]
	v_pk_fma_f32 v[180:181], v[230:231], v[74:75], v[92:93] op_sel:[0,1,0] neg_lo:[1,0,0] neg_hi:[1,0,0]
	v_pk_fma_f32 v[182:183], v[230:231], v[76:77], v[94:95] op_sel_hi:[1,0,1] neg_lo:[1,0,0] neg_hi:[1,0,0]
	v_pk_fma_f32 v[184:185], v[230:231], v[76:77], v[96:97] op_sel:[0,1,0] neg_lo:[1,0,0] neg_hi:[1,0,0]
	v_pk_fma_f32 v[234:235], v[78:79], v[80:81], v[234:235] op_sel:[0,1,0]
	ds_read_b128 v[218:221], v240 offset:49408
	ds_read_b128 v[222:225], v240 offset:49424
	ds_read_b64 v[228:229], v243 offset:8
	s_mov_b64 exec, s[60:61]
	ds_write_b64 v242, v[234:235] offset:16384
	s_mov_b64 exec, -1
	s_waitcnt lgkmcnt(9)
; __device__ __forceinline__ void phase_rw_scan(KP P, const Ctx& c) {
;     ...
;             RW_LLOAD(A, 0);
; #pragma unroll 1
;             for (int tk = 0; tk < 64; tk += 2) {
;                 RW_LLOAD(B, tk + 1);
;                 RW_STEP(A, tk);
;                 RW_LLOAD(A, (tk + 2) & 63);
;                 RW_STEP(B, tk + 1);
;             }
	v_pk_mul_f32 v[230:231], v[170:171], v[186:187] op_sel_hi:[1,0]
	v_pk_mul_f32 v[232:233], v[170:171], v[194:195] op_sel_hi:[1,0]
	v_pk_fma_f32 v[230:231], v[172:173], v[186:187], v[230:231] op_sel:[0,1,0]
	v_pk_fma_f32 v[232:233], v[172:173], v[194:195], v[232:233] op_sel:[0,1,0]
	v_pk_fma_f32 v[230:231], v[174:175], v[188:189], v[230:231] op_sel_hi:[1,0,1]
	v_pk_fma_f32 v[232:233], v[174:175], v[196:197], v[232:233] op_sel_hi:[1,0,1]
	v_pk_fma_f32 v[230:231], v[176:177], v[188:189], v[230:231] op_sel:[0,1,0]
	v_pk_fma_f32 v[232:233], v[176:177], v[196:197], v[232:233] op_sel:[0,1,0]
	v_pk_fma_f32 v[230:231], v[178:179], v[190:191], v[230:231] op_sel_hi:[1,0,1]
	v_pk_fma_f32 v[232:233], v[178:179], v[198:199], v[232:233] op_sel_hi:[1,0,1]
	v_pk_fma_f32 v[230:231], v[180:181], v[190:191], v[230:231] op_sel:[0,1,0]
	v_pk_fma_f32 v[232:233], v[180:181], v[198:199], v[232:233] op_sel:[0,1,0]
	v_pk_fma_f32 v[230:231], v[182:183], v[192:193], v[230:231] op_sel_hi:[1,0,1]
	v_pk_fma_f32 v[232:233], v[182:183], v[200:201], v[232:233] op_sel_hi:[1,0,1]
	v_pk_fma_f32 v[230:231], v[184:185], v[192:193], v[230:231] op_sel:[0,1,0]
	v_pk_fma_f32 v[232:233], v[184:185], v[200:201], v[232:233] op_sel:[0,1,0]
	ds_read_b128 v[38:41], v240 offset:33280
	ds_read_b128 v[42:45], v240 offset:33296
	ds_read_b128 v[46:49], v240 offset:512
	ds_read_b128 v[50:53], v240 offset:528
	s_waitcnt lgkmcnt(8)
	v_pk_mul_f32 v[82:83], v[170:171], v[202:203] op_sel_hi:[1,0]
	v_pk_mul_f32 v[84:85], v[172:173], v[202:203] op_sel:[0,1]
	v_pk_mul_f32 v[86:87], v[174:175], v[204:205] op_sel_hi:[1,0]
	v_pk_mul_f32 v[88:89], v[176:177], v[204:205] op_sel:[0,1]
	v_add_f32_dpp v230, v230, v230 quad_perm:[1,0,3,2] row_mask:0xf bank_mask:0xf
	v_pk_mul_f32 v[90:91], v[178:179], v[206:207] op_sel_hi:[1,0]
	v_add_f32_dpp v231, v231, v231 quad_perm:[1,0,3,2] row_mask:0xf bank_mask:0xf
	v_pk_mul_f32 v[92:93], v[180:181], v[206:207] op_sel:[0,1]
	v_add_f32_dpp v232, v232, v232 quad_perm:[1,0,3,2] row_mask:0xf bank_mask:0xf
	v_pk_mul_f32 v[94:95], v[182:183], v[208:209] op_sel_hi:[1,0]
	v_add_f32_dpp v233, v233, v233 quad_perm:[1,0,3,2] row_mask:0xf bank_mask:0xf
	v_pk_mul_f32 v[96:97], v[184:185], v[208:209] op_sel:[0,1]
	v_add_f32_dpp v230, v230, v230 quad_perm:[2,3,0,1] row_mask:0xf bank_mask:0xf
	v_pk_fma_f32 v[82:83], v[226:227], v[210:211], v[82:83] op_sel_hi:[1,0,1]
	v_add_f32_dpp v231, v231, v231 quad_perm:[2,3,0,1] row_mask:0xf bank_mask:0xf
	v_pk_fma_f32 v[84:85], v[226:227], v[210:211], v[84:85] op_sel:[0,1,0]
	v_add_f32_dpp v232, v232, v232 quad_perm:[2,3,0,1] row_mask:0xf bank_mask:0xf
	v_pk_fma_f32 v[86:87], v[226:227], v[212:213], v[86:87] op_sel_hi:[1,0,1]
	v_add_f32_dpp v233, v233, v233 quad_perm:[2,3,0,1] row_mask:0xf bank_mask:0xf
	v_pk_fma_f32 v[88:89], v[226:227], v[212:213], v[88:89] op_sel:[0,1,0]
	v_add_f32_dpp v230, v230, v230 row_half_mirror row_mask:0xf bank_mask:0xf
	v_pk_fma_f32 v[90:91], v[226:227], v[214:215], v[90:91] op_sel_hi:[1,0,1]
	v_add_f32_dpp v231, v231, v231 row_half_mirror row_mask:0xf bank_mask:0xf
	v_pk_fma_f32 v[92:93], v[226:227], v[214:215], v[92:93] op_sel:[0,1,0]
	v_add_f32_dpp v232, v232, v232 row_half_mirror row_mask:0xf bank_mask:0xf
	v_pk_fma_f32 v[94:95], v[226:227], v[216:217], v[94:95] op_sel_hi:[1,0,1]
	v_add_f32_dpp v233, v233, v233 row_half_mirror row_mask:0xf bank_mask:0xf
	v_pk_fma_f32 v[96:97], v[226:227], v[216:217], v[96:97] op_sel:[0,1,0]
	ds_read_b128 v[54:57], v240 offset:16896
	ds_read_b128 v[58:61], v240 offset:16912
	ds_read_b128 v[62:65], v241 offset:512
	ds_read_b128 v[66:69], v241 offset:528
	ds_read_b64 v[78:79], v242 offset:512
	s_waitcnt lgkmcnt(10)
	v_pk_fma_f32 v[234:235], v[230:231], v[228:229], v[232:233] op_sel_hi:[1,0,1] neg_lo:[1,0,0] neg_hi:[1,0,0]
	v_pk_fma_f32 v[170:171], v[230:231], v[218:219], v[82:83] op_sel_hi:[1,0,1] neg_lo:[1,0,0] neg_hi:[1,0,0]
	v_pk_fma_f32 v[172:173], v[230:231], v[218:219], v[84:85] op_sel:[0,1,0] neg_lo:[1,0,0] neg_hi:[1,0,0]
	v_pk_fma_f32 v[174:175], v[230:231], v[220:221], v[86:87] op_sel_hi:[1,0,1] neg_lo:[1,0,0] neg_hi:[1,0,0]
	v_pk_fma_f32 v[176:177], v[230:231], v[220:221], v[88:89] op_sel:[0,1,0] neg_lo:[1,0,0] neg_hi:[1,0,0]
	v_pk_fma_f32 v[178:179], v[230:231], v[222:223], v[90:91] op_sel_hi:[1,0,1] neg_lo:[1,0,0] neg_hi:[1,0,0]
	v_pk_fma_f32 v[180:181], v[230:231], v[222:223], v[92:93] op_sel:[0,1,0] neg_lo:[1,0,0] neg_hi:[1,0,0]
	v_pk_fma_f32 v[182:183], v[230:231], v[224:225], v[94:95] op_sel_hi:[1,0,1] neg_lo:[1,0,0] neg_hi:[1,0,0]
	v_pk_fma_f32 v[184:185], v[230:231], v[224:225], v[96:97] op_sel:[0,1,0] neg_lo:[1,0,0] neg_hi:[1,0,0]
	v_pk_fma_f32 v[234:235], v[226:227], v[228:229], v[234:235] op_sel:[0,1,0]
	ds_read_b128 v[70:73], v240 offset:49664
	ds_read_b128 v[74:77], v240 offset:49680
	ds_read_b64 v[80:81], v243 offset:16
	s_mov_b64 exec, s[60:61]
	ds_write_b64 v242, v[234:235] offset:16640
	s_mov_b64 exec, -1
	s_waitcnt lgkmcnt(9)
	v_pk_mul_f32 v[230:231], v[170:171], v[38:39] op_sel_hi:[1,0]
	v_pk_mul_f32 v[232:233], v[170:171], v[46:47] op_sel_hi:[1,0]
	v_pk_fma_f32 v[230:231], v[172:173], v[38:39], v[230:231] op_sel:[0,1,0]
	v_pk_fma_f32 v[232:233], v[172:173], v[46:47], v[232:233] op_sel:[0,1,0]
	v_pk_fma_f32 v[230:231], v[174:175], v[40:41], v[230:231] op_sel_hi:[1,0,1]
	v_pk_fma_f32 v[232:233], v[174:175], v[48:49], v[232:233] op_sel_hi:[1,0,1]
	v_pk_fma_f32 v[230:231], v[176:177], v[40:41], v[230:231] op_sel:[0,1,0]
	v_pk_fma_f32 v[232:233], v[176:177], v[48:49], v[232:233] op_sel:[0,1,0]
	v_pk_fma_f32 v[230:231], v[178:179], v[42:43], v[230:231] op_sel_hi:[1,0,1]
	v_pk_fma_f32 v[232:233], v[178:179], v[50:51], v[232:233] op_sel_hi:[1,0,1]
	v_pk_fma_f32 v[230:231], v[180:181], v[42:43], v[230:231] op_sel:[0,1,0]
	v_pk_fma_f32 v[232:233], v[180:181], v[50:51], v[232:233] op_sel:[0,1,0]
	v_pk_fma_f32 v[230:231], v[182:183], v[44:45], v[230:231] op_sel_hi:[1,0,1]
	v_pk_fma_f32 v[232:233], v[182:183], v[52:53], v[232:233] op_sel_hi:[1,0,1]
	v_pk_fma_f32 v[230:231], v[184:185], v[44:45], v[230:231] op_sel:[0,1,0]
	v_pk_fma_f32 v[232:233], v[184:185], v[52:53], v[232:233] op_sel:[0,1,0]
	ds_read_b128 v[186:189], v240 offset:33536
	ds_read_b128 v[190:193], v240 offset:33552
	ds_read_b128 v[194:197], v240 offset:768
	ds_read_b128 v[198:201], v240 offset:784
	s_waitcnt lgkmcnt(8)
; __device__ __forceinline__ void phase_rw_scan(KP P, const Ctx& c) {
;     ...
;             RW_LLOAD(A, 0);
; #pragma unroll 1
;             for (int tk = 0; tk < 64; tk += 2) {
;                 RW_LLOAD(B, tk + 1);
;                 RW_STEP(A, tk);
;                 RW_LLOAD(A, (tk + 2) & 63);
;                 RW_STEP(B, tk + 1);
;             }
	v_pk_mul_f32 v[82:83], v[170:171], v[54:55] op_sel_hi:[1,0]
	v_pk_mul_f32 v[84:85], v[172:173], v[54:55] op_sel:[0,1]
	v_pk_mul_f32 v[86:87], v[174:175], v[56:57] op_sel_hi:[1,0]
	v_pk_mul_f32 v[88:89], v[176:177], v[56:57] op_sel:[0,1]
	v_add_f32_dpp v230, v230, v230 quad_perm:[1,0,3,2] row_mask:0xf bank_mask:0xf
	v_pk_mul_f32 v[90:91], v[178:179], v[58:59] op_sel_hi:[1,0]
	v_add_f32_dpp v231, v231, v231 quad_perm:[1,0,3,2] row_mask:0xf bank_mask:0xf
	v_pk_mul_f32 v[92:93], v[180:181], v[58:59] op_sel:[0,1]
	v_add_f32_dpp v232, v232, v232 quad_perm:[1,0,3,2] row_mask:0xf bank_mask:0xf
	v_pk_mul_f32 v[94:95], v[182:183], v[60:61] op_sel_hi:[1,0]
	v_add_f32_dpp v233, v233, v233 quad_perm:[1,0,3,2] row_mask:0xf bank_mask:0xf
	v_pk_mul_f32 v[96:97], v[184:185], v[60:61] op_sel:[0,1]
	v_add_f32_dpp v230, v230, v230 quad_perm:[2,3,0,1] row_mask:0xf bank_mask:0xf
	v_pk_fma_f32 v[82:83], v[78:79], v[62:63], v[82:83] op_sel_hi:[1,0,1]
	v_add_f32_dpp v231, v231, v231 quad_perm:[2,3,0,1] row_mask:0xf bank_mask:0xf
	v_pk_fma_f32 v[84:85], v[78:79], v[62:63], v[84:85] op_sel:[0,1,0]
	v_add_f32_dpp v232, v232, v232 quad_perm:[2,3,0,1] row_mask:0xf bank_mask:0xf
	v_pk_fma_f32 v[86:87], v[78:79], v[64:65], v[86:87] op_sel_hi:[1,0,1]
	v_add_f32_dpp v233, v233, v233 quad_perm:[2,3,0,1] row_mask:0xf bank_mask:0xf
	v_pk_fma_f32 v[88:89], v[78:79], v[64:65], v[88:89] op_sel:[0,1,0]
	v_add_f32_dpp v230, v230, v230 row_half_mirror row_mask:0xf bank_mask:0xf
	v_pk_fma_f32 v[90:91], v[78:79], v[66:67], v[90:91] op_sel_hi:[1,0,1]
	v_add_f32_dpp v231, v231, v231 row_half_mirror row_mask:0xf bank_mask:0xf
	v_pk_fma_f32 v[92:93], v[78:79], v[66:67], v[92:93] op_sel:[0,1,0]
	v_add_f32_dpp v232, v232, v232 row_half_mirror row_mask:0xf bank_mask:0xf
	v_pk_fma_f32 v[94:95], v[78:79], v[68:69], v[94:95] op_sel_hi:[1,0,1]
	v_add_f32_dpp v233, v233, v233 row_half_mirror row_mask:0xf bank_mask:0xf
	v_pk_fma_f32 v[96:97], v[78:79], v[68:69], v[96:97] op_sel:[0,1,0]
	ds_read_b128 v[202:205], v240 offset:17152
	ds_read_b128 v[206:209], v240 offset:17168
	ds_read_b128 v[210:213], v241 offset:768
	ds_read_b128 v[214:217], v241 offset:784
	ds_read_b64 v[226:227], v242 offset:768
	s_waitcnt lgkmcnt(10)
	v_pk_fma_f32 v[234:235], v[230:231], v[80:81], v[232:233] op_sel_hi:[1,0,1] neg_lo:[1,0,0] neg_hi:[1,0,0]
	v_pk_fma_f32 v[170:171], v[230:231], v[70:71], v[82:83] op_sel_hi:[1,0,1] neg_lo:[1,0,0] neg_hi:[1,0,0]
	v_pk_fma_f32 v[172:173], v[230:231], v[70:71], v[84:85] op_sel:[0,1,0] neg_lo:[1,0,0] neg_hi:[1,0,0]
	v_pk_fma_f32 v[174:175], v[230:231], v[72:73], v[86:87] op_sel_hi:[1,0,1] neg_lo:[1,0,0] neg_hi:[1,0,0]
	v_pk_fma_f32 v[176:177], v[230:231], v[72:73], v[88:89] op_sel:[0,1,0] neg_lo:[1,0,0] neg_hi:[1,0,0]
	v_pk_fma_f32 v[178:179], v[230:231], v[74:75], v[90:91] op_sel_hi:[1,0,1] neg_lo:[1,0,0] neg_hi:[1,0,0]
	v_pk_fma_f32 v[180:181], v[230:231], v[74:75], v[92:93] op_sel:[0,1,0] neg_lo:[1,0,0] neg_hi:[1,0,0]
	v_pk_fma_f32 v[182:183], v[230:231], v[76:77], v[94:95] op_sel_hi:[1,0,1] neg_lo:[1,0,0] neg_hi:[1,0,0]
	v_pk_fma_f32 v[184:185], v[230:231], v[76:77], v[96:97] op_sel:[0,1,0] neg_lo:[1,0,0] neg_hi:[1,0,0]
	v_pk_fma_f32 v[234:235], v[78:79], v[80:81], v[234:235] op_sel:[0,1,0]
	ds_read_b128 v[218:221], v240 offset:49920
	ds_read_b128 v[222:225], v240 offset:49936
	ds_read_b64 v[228:229], v243 offset:24
	s_mov_b64 exec, s[60:61]
	ds_write_b64 v242, v[234:235] offset:16896
	s_mov_b64 exec, -1
	s_waitcnt lgkmcnt(9)
	v_pk_mul_f32 v[230:231], v[170:171], v[186:187] op_sel_hi:[1,0]
	v_pk_mul_f32 v[232:233], v[170:171], v[194:195] op_sel_hi:[1,0]
	v_pk_fma_f32 v[230:231], v[172:173], v[186:187], v[230:231] op_sel:[0,1,0]
	v_pk_fma_f32 v[232:233], v[172:173], v[194:195], v[232:233] op_sel:[0,1,0]
	v_pk_fma_f32 v[230:231], v[174:175], v[188:189], v[230:231] op_sel_hi:[1,0,1]
	v_pk_fma_f32 v[232:233], v[174:175], v[196:197], v[232:233] op_sel_hi:[1,0,1]
	v_pk_fma_f32 v[230:231], v[176:177], v[188:189], v[230:231] op_sel:[0,1,0]
	v_pk_fma_f32 v[232:233], v[176:177], v[196:197], v[232:233] op_sel:[0,1,0]
	v_pk_fma_f32 v[230:231], v[178:179], v[190:191], v[230:231] op_sel_hi:[1,0,1]
	v_pk_fma_f32 v[232:233], v[178:179], v[198:199], v[232:233] op_sel_hi:[1,0,1]
	v_pk_fma_f32 v[230:231], v[180:181], v[190:191], v[230:231] op_sel:[0,1,0]
	v_pk_fma_f32 v[232:233], v[180:181], v[198:199], v[232:233] op_sel:[0,1,0]
	v_pk_fma_f32 v[230:231], v[182:183], v[192:193], v[230:231] op_sel_hi:[1,0,1]
	v_pk_fma_f32 v[232:233], v[182:183], v[200:201], v[232:233] op_sel_hi:[1,0,1]
	v_pk_fma_f32 v[230:231], v[184:185], v[192:193], v[230:231] op_sel:[0,1,0]
	v_pk_fma_f32 v[232:233], v[184:185], v[200:201], v[232:233] op_sel:[0,1,0]
	ds_read_b128 v[38:41], v240 offset:33792
	ds_read_b128 v[42:45], v240 offset:33808
	ds_read_b128 v[46:49], v240 offset:1024
	ds_read_b128 v[50:53], v240 offset:1040
	s_waitcnt lgkmcnt(8)
; __device__ __forceinline__ void phase_rw_scan(KP P, const Ctx& c) {
;     ...
;             RW_LLOAD(A, 0);
; #pragma unroll 1
;             for (int tk = 0; tk < 64; tk += 2) {
;                 RW_LLOAD(B, tk + 1);
;                 RW_STEP(A, tk);
;                 RW_LLOAD(A, (tk + 2) & 63);
;                 RW_STEP(B, tk + 1);
;             }
	v_pk_mul_f32 v[82:83], v[170:171], v[202:203] op_sel_hi:[1,0]
	v_pk_mul_f32 v[84:85], v[172:173], v[202:203] op_sel:[0,1]
	v_pk_mul_f32 v[86:87], v[174:175], v[204:205] op_sel_hi:[1,0]
	v_pk_mul_f32 v[88:89], v[176:177], v[204:205] op_sel:[0,1]
	v_add_f32_dpp v230, v230, v230 quad_perm:[1,0,3,2] row_mask:0xf bank_mask:0xf
	v_pk_mul_f32 v[90:91], v[178:179], v[206:207] op_sel_hi:[1,0]
	v_add_f32_dpp v231, v231, v231 quad_perm:[1,0,3,2] row_mask:0xf bank_mask:0xf
	v_pk_mul_f32 v[92:93], v[180:181], v[206:207] op_sel:[0,1]
	v_add_f32_dpp v232, v232, v232 quad_perm:[1,0,3,2] row_mask:0xf bank_mask:0xf
	v_pk_mul_f32 v[94:95], v[182:183], v[208:209] op_sel_hi:[1,0]
	v_add_f32_dpp v233, v233, v233 quad_perm:[1,0,3,2] row_mask:0xf bank_mask:0xf
	v_pk_mul_f32 v[96:97], v[184:185], v[208:209] op_sel:[0,1]
	v_add_f32_dpp v230, v230, v230 quad_perm:[2,3,0,1] row_mask:0xf bank_mask:0xf
	v_pk_fma_f32 v[82:83], v[226:227], v[210:211], v[82:83] op_sel_hi:[1,0,1]
	v_add_f32_dpp v231, v231, v231 quad_perm:[2,3,0,1] row_mask:0xf bank_mask:0xf
	v_pk_fma_f32 v[84:85], v[226:227], v[210:211], v[84:85] op_sel:[0,1,0]
	v_add_f32_dpp v232, v232, v232 quad_perm:[2,3,0,1] row_mask:0xf bank_mask:0xf
	v_pk_fma_f32 v[86:87], v[226:227], v[212:213], v[86:87] op_sel_hi:[1,0,1]
	v_add_f32_dpp v233, v233, v233 quad_perm:[2,3,0,1] row_mask:0xf bank_mask:0xf
	v_pk_fma_f32 v[88:89], v[226:227], v[212:213], v[88:89] op_sel:[0,1,0]
	v_add_f32_dpp v230, v230, v230 row_half_mirror row_mask:0xf bank_mask:0xf
	v_pk_fma_f32 v[90:91], v[226:227], v[214:215], v[90:91] op_sel_hi:[1,0,1]
	v_add_f32_dpp v231, v231, v231 row_half_mirror row_mask:0xf bank_mask:0xf
	v_pk_fma_f32 v[92:93], v[226:227], v[214:215], v[92:93] op_sel:[0,1,0]
	v_add_f32_dpp v232, v232, v232 row_half_mirror row_mask:0xf bank_mask:0xf
	v_pk_fma_f32 v[94:95], v[226:227], v[216:217], v[94:95] op_sel_hi:[1,0,1]
	v_add_f32_dpp v233, v233, v233 row_half_mirror row_mask:0xf bank_mask:0xf
	v_pk_fma_f32 v[96:97], v[226:227], v[216:217], v[96:97] op_sel:[0,1,0]
	ds_read_b128 v[54:57], v240 offset:17408
	ds_read_b128 v[58:61], v240 offset:17424
	ds_read_b128 v[62:65], v241 offset:1024
	ds_read_b128 v[66:69], v241 offset:1040
	ds_read_b64 v[78:79], v242 offset:1024
	s_waitcnt lgkmcnt(10)
	v_pk_fma_f32 v[234:235], v[230:231], v[228:229], v[232:233] op_sel_hi:[1,0,1] neg_lo:[1,0,0] neg_hi:[1,0,0]
	v_pk_fma_f32 v[170:171], v[230:231], v[218:219], v[82:83] op_sel_hi:[1,0,1] neg_lo:[1,0,0] neg_hi:[1,0,0]
	v_pk_fma_f32 v[172:173], v[230:231], v[218:219], v[84:85] op_sel:[0,1,0] neg_lo:[1,0,0] neg_hi:[1,0,0]
	v_pk_fma_f32 v[174:175], v[230:231], v[220:221], v[86:87] op_sel_hi:[1,0,1] neg_lo:[1,0,0] neg_hi:[1,0,0]
	v_pk_fma_f32 v[176:177], v[230:231], v[220:221], v[88:89] op_sel:[0,1,0] neg_lo:[1,0,0] neg_hi:[1,0,0]
	v_pk_fma_f32 v[178:179], v[230:231], v[222:223], v[90:91] op_sel_hi:[1,0,1] neg_lo:[1,0,0] neg_hi:[1,0,0]
	v_pk_fma_f32 v[180:181], v[230:231], v[222:223], v[92:93] op_sel:[0,1,0] neg_lo:[1,0,0] neg_hi:[1,0,0]
	v_pk_fma_f32 v[182:183], v[230:231], v[224:225], v[94:95] op_sel_hi:[1,0,1] neg_lo:[1,0,0] neg_hi:[1,0,0]
	v_pk_fma_f32 v[184:185], v[230:231], v[224:225], v[96:97] op_sel:[0,1,0] neg_lo:[1,0,0] neg_hi:[1,0,0]
	v_pk_fma_f32 v[234:235], v[226:227], v[228:229], v[234:235] op_sel:[0,1,0]
	ds_read_b128 v[70:73], v240 offset:50176
	ds_read_b128 v[74:77], v240 offset:50192
	ds_read_b64 v[80:81], v243 offset:32
	s_mov_b64 exec, s[60:61]
	ds_write_b64 v242, v[234:235] offset:17152
	s_mov_b64 exec, -1
	s_waitcnt lgkmcnt(9)
	v_pk_mul_f32 v[230:231], v[170:171], v[38:39] op_sel_hi:[1,0]
	v_pk_mul_f32 v[232:233], v[170:171], v[46:47] op_sel_hi:[1,0]
	v_pk_fma_f32 v[230:231], v[172:173], v[38:39], v[230:231] op_sel:[0,1,0]
	v_pk_fma_f32 v[232:233], v[172:173], v[46:47], v[232:233] op_sel:[0,1,0]
	v_pk_fma_f32 v[230:231], v[174:175], v[40:41], v[230:231] op_sel_hi:[1,0,1]
	v_pk_fma_f32 v[232:233], v[174:175], v[48:49], v[232:233] op_sel_hi:[1,0,1]
	v_pk_fma_f32 v[230:231], v[176:177], v[40:41], v[230:231] op_sel:[0,1,0]
	v_pk_fma_f32 v[232:233], v[176:177], v[48:49], v[232:233] op_sel:[0,1,0]
	v_pk_fma_f32 v[230:231], v[178:179], v[42:43], v[230:231] op_sel_hi:[1,0,1]
	v_pk_fma_f32 v[232:233], v[178:179], v[50:51], v[232:233] op_sel_hi:[1,0,1]
	v_pk_fma_f32 v[230:231], v[180:181], v[42:43], v[230:231] op_sel:[0,1,0]
	v_pk_fma_f32 v[232:233], v[180:181], v[50:51], v[232:233] op_sel:[0,1,0]
	v_pk_fma_f32 v[230:231], v[182:183], v[44:45], v[230:231] op_sel_hi:[1,0,1]
	v_pk_fma_f32 v[232:233], v[182:183], v[52:53], v[232:233] op_sel_hi:[1,0,1]
	v_pk_fma_f32 v[230:231], v[184:185], v[44:45], v[230:231] op_sel:[0,1,0]
	v_pk_fma_f32 v[232:233], v[184:185], v[52:53], v[232:233] op_sel:[0,1,0]
	ds_read_b128 v[186:189], v240 offset:34048
	ds_read_b128 v[190:193], v240 offset:34064
	ds_read_b128 v[194:197], v240 offset:1280
	ds_read_b128 v[198:201], v240 offset:1296
	s_waitcnt lgkmcnt(8)
; __device__ __forceinline__ void phase_rw_scan(KP P, const Ctx& c) {
;     ...
;             RW_LLOAD(A, 0);
; #pragma unroll 1
;             for (int tk = 0; tk < 64; tk += 2) {
;                 RW_LLOAD(B, tk + 1);
;                 RW_STEP(A, tk);
;                 RW_LLOAD(A, (tk + 2) & 63);
;                 RW_STEP(B, tk + 1);
;             }
	v_pk_mul_f32 v[82:83], v[170:171], v[54:55] op_sel_hi:[1,0]
	v_pk_mul_f32 v[84:85], v[172:173], v[54:55] op_sel:[0,1]
	v_pk_mul_f32 v[86:87], v[174:175], v[56:57] op_sel_hi:[1,0]
	v_pk_mul_f32 v[88:89], v[176:177], v[56:57] op_sel:[0,1]
	v_add_f32_dpp v230, v230, v230 quad_perm:[1,0,3,2] row_mask:0xf bank_mask:0xf
	v_pk_mul_f32 v[90:91], v[178:179], v[58:59] op_sel_hi:[1,0]
	v_add_f32_dpp v231, v231, v231 quad_perm:[1,0,3,2] row_mask:0xf bank_mask:0xf
	v_pk_mul_f32 v[92:93], v[180:181], v[58:59] op_sel:[0,1]
	v_add_f32_dpp v232, v232, v232 quad_perm:[1,0,3,2] row_mask:0xf bank_mask:0xf
	v_pk_mul_f32 v[94:95], v[182:183], v[60:61] op_sel_hi:[1,0]
	v_add_f32_dpp v233, v233, v233 quad_perm:[1,0,3,2] row_mask:0xf bank_mask:0xf
	v_pk_mul_f32 v[96:97], v[184:185], v[60:61] op_sel:[0,1]
	v_add_f32_dpp v230, v230, v230 quad_perm:[2,3,0,1] row_mask:0xf bank_mask:0xf
	v_pk_fma_f32 v[82:83], v[78:79], v[62:63], v[82:83] op_sel_hi:[1,0,1]
	v_add_f32_dpp v231, v231, v231 quad_perm:[2,3,0,1] row_mask:0xf bank_mask:0xf
	v_pk_fma_f32 v[84:85], v[78:79], v[62:63], v[84:85] op_sel:[0,1,0]
	v_add_f32_dpp v232, v232, v232 quad_perm:[2,3,0,1] row_mask:0xf bank_mask:0xf
	v_pk_fma_f32 v[86:87], v[78:79], v[64:65], v[86:87] op_sel_hi:[1,0,1]
	v_add_f32_dpp v233, v233, v233 quad_perm:[2,3,0,1] row_mask:0xf bank_mask:0xf
	v_pk_fma_f32 v[88:89], v[78:79], v[64:65], v[88:89] op_sel:[0,1,0]
	v_add_f32_dpp v230, v230, v230 row_half_mirror row_mask:0xf bank_mask:0xf
	v_pk_fma_f32 v[90:91], v[78:79], v[66:67], v[90:91] op_sel_hi:[1,0,1]
	v_add_f32_dpp v231, v231, v231 row_half_mirror row_mask:0xf bank_mask:0xf
	v_pk_fma_f32 v[92:93], v[78:79], v[66:67], v[92:93] op_sel:[0,1,0]
	v_add_f32_dpp v232, v232, v232 row_half_mirror row_mask:0xf bank_mask:0xf
	v_pk_fma_f32 v[94:95], v[78:79], v[68:69], v[94:95] op_sel_hi:[1,0,1]
	v_add_f32_dpp v233, v233, v233 row_half_mirror row_mask:0xf bank_mask:0xf
	v_pk_fma_f32 v[96:97], v[78:79], v[68:69], v[96:97] op_sel:[0,1,0]
	ds_read_b128 v[202:205], v240 offset:17664
	ds_read_b128 v[206:209], v240 offset:17680
	ds_read_b128 v[210:213], v241 offset:1280
	ds_read_b128 v[214:217], v241 offset:1296
	ds_read_b64 v[226:227], v242 offset:1280
	s_waitcnt lgkmcnt(10)
	v_pk_fma_f32 v[234:235], v[230:231], v[80:81], v[232:233] op_sel_hi:[1,0,1] neg_lo:[1,0,0] neg_hi:[1,0,0]
	v_pk_fma_f32 v[170:171], v[230:231], v[70:71], v[82:83] op_sel_hi:[1,0,1] neg_lo:[1,0,0] neg_hi:[1,0,0]
	v_pk_fma_f32 v[172:173], v[230:231], v[70:71], v[84:85] op_sel:[0,1,0] neg_lo:[1,0,0] neg_hi:[1,0,0]
	v_pk_fma_f32 v[174:175], v[230:231], v[72:73], v[86:87] op_sel_hi:[1,0,1] neg_lo:[1,0,0] neg_hi:[1,0,0]
	v_pk_fma_f32 v[176:177], v[230:231], v[72:73], v[88:89] op_sel:[0,1,0] neg_lo:[1,0,0] neg_hi:[1,0,0]
	v_pk_fma_f32 v[178:179], v[230:231], v[74:75], v[90:91] op_sel_hi:[1,0,1] neg_lo:[1,0,0] neg_hi:[1,0,0]
	v_pk_fma_f32 v[180:181], v[230:231], v[74:75], v[92:93] op_sel:[0,1,0] neg_lo:[1,0,0] neg_hi:[1,0,0]
	v_pk_fma_f32 v[182:183], v[230:231], v[76:77], v[94:95] op_sel_hi:[1,0,1] neg_lo:[1,0,0] neg_hi:[1,0,0]
	v_pk_fma_f32 v[184:185], v[230:231], v[76:77], v[96:97] op_sel:[0,1,0] neg_lo:[1,0,0] neg_hi:[1,0,0]
	v_pk_fma_f32 v[234:235], v[78:79], v[80:81], v[234:235] op_sel:[0,1,0]
	ds_read_b128 v[218:221], v240 offset:50432
	ds_read_b128 v[222:225], v240 offset:50448
	ds_read_b64 v[228:229], v243 offset:40
	s_mov_b64 exec, s[60:61]
	ds_write_b64 v242, v[234:235] offset:17408
	s_mov_b64 exec, -1
	s_waitcnt lgkmcnt(9)
	v_pk_mul_f32 v[230:231], v[170:171], v[186:187] op_sel_hi:[1,0]
	v_pk_mul_f32 v[232:233], v[170:171], v[194:195] op_sel_hi:[1,0]
	v_pk_fma_f32 v[230:231], v[172:173], v[186:187], v[230:231] op_sel:[0,1,0]
	v_pk_fma_f32 v[232:233], v[172:173], v[194:195], v[232:233] op_sel:[0,1,0]
	v_pk_fma_f32 v[230:231], v[174:175], v[188:189], v[230:231] op_sel_hi:[1,0,1]
	v_pk_fma_f32 v[232:233], v[174:175], v[196:197], v[232:233] op_sel_hi:[1,0,1]
	v_pk_fma_f32 v[230:231], v[176:177], v[188:189], v[230:231] op_sel:[0,1,0]
	v_pk_fma_f32 v[232:233], v[176:177], v[196:197], v[232:233] op_sel:[0,1,0]
	v_pk_fma_f32 v[230:231], v[178:179], v[190:191], v[230:231] op_sel_hi:[1,0,1]
	v_pk_fma_f32 v[232:233], v[178:179], v[198:199], v[232:233] op_sel_hi:[1,0,1]
	v_pk_fma_f32 v[230:231], v[180:181], v[190:191], v[230:231] op_sel:[0,1,0]
	v_pk_fma_f32 v[232:233], v[180:181], v[198:199], v[232:233] op_sel:[0,1,0]
	v_pk_fma_f32 v[230:231], v[182:183], v[192:193], v[230:231] op_sel_hi:[1,0,1]
	v_pk_fma_f32 v[232:233], v[182:183], v[200:201], v[232:233] op_sel_hi:[1,0,1]
	v_pk_fma_f32 v[230:231], v[184:185], v[192:193], v[230:231] op_sel:[0,1,0]
	v_pk_fma_f32 v[232:233], v[184:185], v[200:201], v[232:233] op_sel:[0,1,0]
	ds_read_b128 v[38:41], v240 offset:34304
	ds_read_b128 v[42:45], v240 offset:34320
	ds_read_b128 v[46:49], v240 offset:1536
	ds_read_b128 v[50:53], v240 offset:1552
	s_waitcnt lgkmcnt(8)
; __device__ __forceinline__ void phase_rw_scan(KP P, const Ctx& c) {
;     ...
;             RW_LLOAD(A, 0);
; #pragma unroll 1
;             for (int tk = 0; tk < 64; tk += 2) {
;                 RW_LLOAD(B, tk + 1);
;                 RW_STEP(A, tk);
;                 RW_LLOAD(A, (tk + 2) & 63);
;                 RW_STEP(B, tk + 1);
;             }
	v_pk_mul_f32 v[82:83], v[170:171], v[202:203] op_sel_hi:[1,0]
	v_pk_mul_f32 v[84:85], v[172:173], v[202:203] op_sel:[0,1]
	v_pk_mul_f32 v[86:87], v[174:175], v[204:205] op_sel_hi:[1,0]
	v_pk_mul_f32 v[88:89], v[176:177], v[204:205] op_sel:[0,1]
	v_add_f32_dpp v230, v230, v230 quad_perm:[1,0,3,2] row_mask:0xf bank_mask:0xf
	v_pk_mul_f32 v[90:91], v[178:179], v[206:207] op_sel_hi:[1,0]
	v_add_f32_dpp v231, v231, v231 quad_perm:[1,0,3,2] row_mask:0xf bank_mask:0xf
	v_pk_mul_f32 v[92:93], v[180:181], v[206:207] op_sel:[0,1]
	v_add_f32_dpp v232, v232, v232 quad_perm:[1,0,3,2] row_mask:0xf bank_mask:0xf
	v_pk_mul_f32 v[94:95], v[182:183], v[208:209] op_sel_hi:[1,0]
	v_add_f32_dpp v233, v233, v233 quad_perm:[1,0,3,2] row_mask:0xf bank_mask:0xf
	v_pk_mul_f32 v[96:97], v[184:185], v[208:209] op_sel:[0,1]
	v_add_f32_dpp v230, v230, v230 quad_perm:[2,3,0,1] row_mask:0xf bank_mask:0xf
	v_pk_fma_f32 v[82:83], v[226:227], v[210:211], v[82:83] op_sel_hi:[1,0,1]
	v_add_f32_dpp v231, v231, v231 quad_perm:[2,3,0,1] row_mask:0xf bank_mask:0xf
	v_pk_fma_f32 v[84:85], v[226:227], v[210:211], v[84:85] op_sel:[0,1,0]
	v_add_f32_dpp v232, v232, v232 quad_perm:[2,3,0,1] row_mask:0xf bank_mask:0xf
	v_pk_fma_f32 v[86:87], v[226:227], v[212:213], v[86:87] op_sel_hi:[1,0,1]
	v_add_f32_dpp v233, v233, v233 quad_perm:[2,3,0,1] row_mask:0xf bank_mask:0xf
	v_pk_fma_f32 v[88:89], v[226:227], v[212:213], v[88:89] op_sel:[0,1,0]
	v_add_f32_dpp v230, v230, v230 row_half_mirror row_mask:0xf bank_mask:0xf
	v_pk_fma_f32 v[90:91], v[226:227], v[214:215], v[90:91] op_sel_hi:[1,0,1]
	v_add_f32_dpp v231, v231, v231 row_half_mirror row_mask:0xf bank_mask:0xf
	v_pk_fma_f32 v[92:93], v[226:227], v[214:215], v[92:93] op_sel:[0,1,0]
	v_add_f32_dpp v232, v232, v232 row_half_mirror row_mask:0xf bank_mask:0xf
	v_pk_fma_f32 v[94:95], v[226:227], v[216:217], v[94:95] op_sel_hi:[1,0,1]
	v_add_f32_dpp v233, v233, v233 row_half_mirror row_mask:0xf bank_mask:0xf
	v_pk_fma_f32 v[96:97], v[226:227], v[216:217], v[96:97] op_sel:[0,1,0]
	ds_read_b128 v[54:57], v240 offset:17920
	ds_read_b128 v[58:61], v240 offset:17936
	ds_read_b128 v[62:65], v241 offset:1536
	ds_read_b128 v[66:69], v241 offset:1552
	ds_read_b64 v[78:79], v242 offset:1536
	s_waitcnt lgkmcnt(10)
	v_pk_fma_f32 v[234:235], v[230:231], v[228:229], v[232:233] op_sel_hi:[1,0,1] neg_lo:[1,0,0] neg_hi:[1,0,0]
	v_pk_fma_f32 v[170:171], v[230:231], v[218:219], v[82:83] op_sel_hi:[1,0,1] neg_lo:[1,0,0] neg_hi:[1,0,0]
	v_pk_fma_f32 v[172:173], v[230:231], v[218:219], v[84:85] op_sel:[0,1,0] neg_lo:[1,0,0] neg_hi:[1,0,0]
	v_pk_fma_f32 v[174:175], v[230:231], v[220:221], v[86:87] op_sel_hi:[1,0,1] neg_lo:[1,0,0] neg_hi:[1,0,0]
	v_pk_fma_f32 v[176:177], v[230:231], v[220:221], v[88:89] op_sel:[0,1,0] neg_lo:[1,0,0] neg_hi:[1,0,0]
	v_pk_fma_f32 v[178:179], v[230:231], v[222:223], v[90:91] op_sel_hi:[1,0,1] neg_lo:[1,0,0] neg_hi:[1,0,0]
	v_pk_fma_f32 v[180:181], v[230:231], v[222:223], v[92:93] op_sel:[0,1,0] neg_lo:[1,0,0] neg_hi:[1,0,0]
	v_pk_fma_f32 v[182:183], v[230:231], v[224:225], v[94:95] op_sel_hi:[1,0,1] neg_lo:[1,0,0] neg_hi:[1,0,0]
	v_pk_fma_f32 v[184:185], v[230:231], v[224:225], v[96:97] op_sel:[0,1,0] neg_lo:[1,0,0] neg_hi:[1,0,0]
	v_pk_fma_f32 v[234:235], v[226:227], v[228:229], v[234:235] op_sel:[0,1,0]
	ds_read_b128 v[70:73], v240 offset:50688
	ds_read_b128 v[74:77], v240 offset:50704
	ds_read_b64 v[80:81], v243 offset:48
	s_mov_b64 exec, s[60:61]
	ds_write_b64 v242, v[234:235] offset:17664
	s_mov_b64 exec, -1
	s_waitcnt lgkmcnt(9)
	v_pk_mul_f32 v[230:231], v[170:171], v[38:39] op_sel_hi:[1,0]
	v_pk_mul_f32 v[232:233], v[170:171], v[46:47] op_sel_hi:[1,0]
	v_pk_fma_f32 v[230:231], v[172:173], v[38:39], v[230:231] op_sel:[0,1,0]
	v_pk_fma_f32 v[232:233], v[172:173], v[46:47], v[232:233] op_sel:[0,1,0]
	v_pk_fma_f32 v[230:231], v[174:175], v[40:41], v[230:231] op_sel_hi:[1,0,1]
	v_pk_fma_f32 v[232:233], v[174:175], v[48:49], v[232:233] op_sel_hi:[1,0,1]
	v_pk_fma_f32 v[230:231], v[176:177], v[40:41], v[230:231] op_sel:[0,1,0]
	v_pk_fma_f32 v[232:233], v[176:177], v[48:49], v[232:233] op_sel:[0,1,0]
	v_pk_fma_f32 v[230:231], v[178:179], v[42:43], v[230:231] op_sel_hi:[1,0,1]
	v_pk_fma_f32 v[232:233], v[178:179], v[50:51], v[232:233] op_sel_hi:[1,0,1]
	v_pk_fma_f32 v[230:231], v[180:181], v[42:43], v[230:231] op_sel:[0,1,0]
	v_pk_fma_f32 v[232:233], v[180:181], v[50:51], v[232:233] op_sel:[0,1,0]
	v_pk_fma_f32 v[230:231], v[182:183], v[44:45], v[230:231] op_sel_hi:[1,0,1]
	v_pk_fma_f32 v[232:233], v[182:183], v[52:53], v[232:233] op_sel_hi:[1,0,1]
	v_pk_fma_f32 v[230:231], v[184:185], v[44:45], v[230:231] op_sel:[0,1,0]
	v_pk_fma_f32 v[232:233], v[184:185], v[52:53], v[232:233] op_sel:[0,1,0]
	ds_read_b128 v[186:189], v240 offset:34560
	ds_read_b128 v[190:193], v240 offset:34576
	ds_read_b128 v[194:197], v240 offset:1792
	ds_read_b128 v[198:201], v240 offset:1808
	s_waitcnt lgkmcnt(8)
; __device__ __forceinline__ void phase_rw_scan(KP P, const Ctx& c) {
;     ...
;             RW_LLOAD(A, 0);
; #pragma unroll 1
;             for (int tk = 0; tk < 64; tk += 2) {
;                 RW_LLOAD(B, tk + 1);
;                 RW_STEP(A, tk);
;                 RW_LLOAD(A, (tk + 2) & 63);
;                 RW_STEP(B, tk + 1);
;             }
	v_pk_mul_f32 v[82:83], v[170:171], v[54:55] op_sel_hi:[1,0]
	v_pk_mul_f32 v[84:85], v[172:173], v[54:55] op_sel:[0,1]
	v_pk_mul_f32 v[86:87], v[174:175], v[56:57] op_sel_hi:[1,0]
	v_pk_mul_f32 v[88:89], v[176:177], v[56:57] op_sel:[0,1]
	v_add_f32_dpp v230, v230, v230 quad_perm:[1,0,3,2] row_mask:0xf bank_mask:0xf
	v_pk_mul_f32 v[90:91], v[178:179], v[58:59] op_sel_hi:[1,0]
	v_add_f32_dpp v231, v231, v231 quad_perm:[1,0,3,2] row_mask:0xf bank_mask:0xf
	v_pk_mul_f32 v[92:93], v[180:181], v[58:59] op_sel:[0,1]
	v_add_f32_dpp v232, v232, v232 quad_perm:[1,0,3,2] row_mask:0xf bank_mask:0xf
	v_pk_mul_f32 v[94:95], v[182:183], v[60:61] op_sel_hi:[1,0]
	v_add_f32_dpp v233, v233, v233 quad_perm:[1,0,3,2] row_mask:0xf bank_mask:0xf
	v_pk_mul_f32 v[96:97], v[184:185], v[60:61] op_sel:[0,1]
	v_add_f32_dpp v230, v230, v230 quad_perm:[2,3,0,1] row_mask:0xf bank_mask:0xf
	v_pk_fma_f32 v[82:83], v[78:79], v[62:63], v[82:83] op_sel_hi:[1,0,1]
	v_add_f32_dpp v231, v231, v231 quad_perm:[2,3,0,1] row_mask:0xf bank_mask:0xf
	v_pk_fma_f32 v[84:85], v[78:79], v[62:63], v[84:85] op_sel:[0,1,0]
	v_add_f32_dpp v232, v232, v232 quad_perm:[2,3,0,1] row_mask:0xf bank_mask:0xf
	v_pk_fma_f32 v[86:87], v[78:79], v[64:65], v[86:87] op_sel_hi:[1,0,1]
	v_add_f32_dpp v233, v233, v233 quad_perm:[2,3,0,1] row_mask:0xf bank_mask:0xf
	v_pk_fma_f32 v[88:89], v[78:79], v[64:65], v[88:89] op_sel:[0,1,0]
	v_add_f32_dpp v230, v230, v230 row_half_mirror row_mask:0xf bank_mask:0xf
	v_pk_fma_f32 v[90:91], v[78:79], v[66:67], v[90:91] op_sel_hi:[1,0,1]
	v_add_f32_dpp v231, v231, v231 row_half_mirror row_mask:0xf bank_mask:0xf
	v_pk_fma_f32 v[92:93], v[78:79], v[66:67], v[92:93] op_sel:[0,1,0]
	v_add_f32_dpp v232, v232, v232 row_half_mirror row_mask:0xf bank_mask:0xf
	v_pk_fma_f32 v[94:95], v[78:79], v[68:69], v[94:95] op_sel_hi:[1,0,1]
	v_add_f32_dpp v233, v233, v233 row_half_mirror row_mask:0xf bank_mask:0xf
	v_pk_fma_f32 v[96:97], v[78:79], v[68:69], v[96:97] op_sel:[0,1,0]
	ds_read_b128 v[202:205], v240 offset:18176
	ds_read_b128 v[206:209], v240 offset:18192
	ds_read_b128 v[210:213], v241 offset:1792
	ds_read_b128 v[214:217], v241 offset:1808
	ds_read_b64 v[226:227], v242 offset:1792
	s_waitcnt lgkmcnt(10)
	v_pk_fma_f32 v[234:235], v[230:231], v[80:81], v[232:233] op_sel_hi:[1,0,1] neg_lo:[1,0,0] neg_hi:[1,0,0]
	v_pk_fma_f32 v[170:171], v[230:231], v[70:71], v[82:83] op_sel_hi:[1,0,1] neg_lo:[1,0,0] neg_hi:[1,0,0]
	v_pk_fma_f32 v[172:173], v[230:231], v[70:71], v[84:85] op_sel:[0,1,0] neg_lo:[1,0,0] neg_hi:[1,0,0]
	v_pk_fma_f32 v[174:175], v[230:231], v[72:73], v[86:87] op_sel_hi:[1,0,1] neg_lo:[1,0,0] neg_hi:[1,0,0]
	v_pk_fma_f32 v[176:177], v[230:231], v[72:73], v[88:89] op_sel:[0,1,0] neg_lo:[1,0,0] neg_hi:[1,0,0]
	v_pk_fma_f32 v[178:179], v[230:231], v[74:75], v[90:91] op_sel_hi:[1,0,1] neg_lo:[1,0,0] neg_hi:[1,0,0]
	v_pk_fma_f32 v[180:181], v[230:231], v[74:75], v[92:93] op_sel:[0,1,0] neg_lo:[1,0,0] neg_hi:[1,0,0]
	v_pk_fma_f32 v[182:183], v[230:231], v[76:77], v[94:95] op_sel_hi:[1,0,1] neg_lo:[1,0,0] neg_hi:[1,0,0]
	v_pk_fma_f32 v[184:185], v[230:231], v[76:77], v[96:97] op_sel:[0,1,0] neg_lo:[1,0,0] neg_hi:[1,0,0]
	v_pk_fma_f32 v[234:235], v[78:79], v[80:81], v[234:235] op_sel:[0,1,0]
	ds_read_b128 v[218:221], v240 offset:50944
	ds_read_b128 v[222:225], v240 offset:50960
	ds_read_b64 v[228:229], v243 offset:56
	s_mov_b64 exec, s[60:61]
	ds_write_b64 v242, v[234:235] offset:17920
	s_mov_b64 exec, -1
	s_waitcnt lgkmcnt(9)
	v_pk_mul_f32 v[230:231], v[170:171], v[186:187] op_sel_hi:[1,0]
	v_pk_mul_f32 v[232:233], v[170:171], v[194:195] op_sel_hi:[1,0]
	v_pk_fma_f32 v[230:231], v[172:173], v[186:187], v[230:231] op_sel:[0,1,0]
	v_pk_fma_f32 v[232:233], v[172:173], v[194:195], v[232:233] op_sel:[0,1,0]
	v_pk_fma_f32 v[230:231], v[174:175], v[188:189], v[230:231] op_sel_hi:[1,0,1]
	v_pk_fma_f32 v[232:233], v[174:175], v[196:197], v[232:233] op_sel_hi:[1,0,1]
	v_pk_fma_f32 v[230:231], v[176:177], v[188:189], v[230:231] op_sel:[0,1,0]
	v_pk_fma_f32 v[232:233], v[176:177], v[196:197], v[232:233] op_sel:[0,1,0]
	v_pk_fma_f32 v[230:231], v[178:179], v[190:191], v[230:231] op_sel_hi:[1,0,1]
	v_pk_fma_f32 v[232:233], v[178:179], v[198:199], v[232:233] op_sel_hi:[1,0,1]
	v_pk_fma_f32 v[230:231], v[180:181], v[190:191], v[230:231] op_sel:[0,1,0]
	v_pk_fma_f32 v[232:233], v[180:181], v[198:199], v[232:233] op_sel:[0,1,0]
	v_pk_fma_f32 v[230:231], v[182:183], v[192:193], v[230:231] op_sel_hi:[1,0,1]
	v_pk_fma_f32 v[232:233], v[182:183], v[200:201], v[232:233] op_sel_hi:[1,0,1]
	v_pk_fma_f32 v[230:231], v[184:185], v[192:193], v[230:231] op_sel:[0,1,0]
	v_pk_fma_f32 v[232:233], v[184:185], v[200:201], v[232:233] op_sel:[0,1,0]
	ds_read_b128 v[38:41], v240 offset:34816
	ds_read_b128 v[42:45], v240 offset:34832
	ds_read_b128 v[46:49], v240 offset:2048
	ds_read_b128 v[50:53], v240 offset:2064
	s_waitcnt lgkmcnt(8)
; __device__ __forceinline__ void phase_rw_scan(KP P, const Ctx& c) {
;     ...
;             RW_LLOAD(A, 0);
; #pragma unroll 1
;             for (int tk = 0; tk < 64; tk += 2) {
;                 RW_LLOAD(B, tk + 1);
;                 RW_STEP(A, tk);
;                 RW_LLOAD(A, (tk + 2) & 63);
;                 RW_STEP(B, tk + 1);
;             }
	v_pk_mul_f32 v[82:83], v[170:171], v[202:203] op_sel_hi:[1,0]
	v_pk_mul_f32 v[84:85], v[172:173], v[202:203] op_sel:[0,1]
	v_pk_mul_f32 v[86:87], v[174:175], v[204:205] op_sel_hi:[1,0]
	v_pk_mul_f32 v[88:89], v[176:177], v[204:205] op_sel:[0,1]
	v_add_f32_dpp v230, v230, v230 quad_perm:[1,0,3,2] row_mask:0xf bank_mask:0xf
	v_pk_mul_f32 v[90:91], v[178:179], v[206:207] op_sel_hi:[1,0]
	v_add_f32_dpp v231, v231, v231 quad_perm:[1,0,3,2] row_mask:0xf bank_mask:0xf
	v_pk_mul_f32 v[92:93], v[180:181], v[206:207] op_sel:[0,1]
	v_add_f32_dpp v232, v232, v232 quad_perm:[1,0,3,2] row_mask:0xf bank_mask:0xf
	v_pk_mul_f32 v[94:95], v[182:183], v[208:209] op_sel_hi:[1,0]
	v_add_f32_dpp v233, v233, v233 quad_perm:[1,0,3,2] row_mask:0xf bank_mask:0xf
	v_pk_mul_f32 v[96:97], v[184:185], v[208:209] op_sel:[0,1]
	v_add_f32_dpp v230, v230, v230 quad_perm:[2,3,0,1] row_mask:0xf bank_mask:0xf
	v_pk_fma_f32 v[82:83], v[226:227], v[210:211], v[82:83] op_sel_hi:[1,0,1]
	v_add_f32_dpp v231, v231, v231 quad_perm:[2,3,0,1] row_mask:0xf bank_mask:0xf
	v_pk_fma_f32 v[84:85], v[226:227], v[210:211], v[84:85] op_sel:[0,1,0]
	v_add_f32_dpp v232, v232, v232 quad_perm:[2,3,0,1] row_mask:0xf bank_mask:0xf
	v_pk_fma_f32 v[86:87], v[226:227], v[212:213], v[86:87] op_sel_hi:[1,0,1]
	v_add_f32_dpp v233, v233, v233 quad_perm:[2,3,0,1] row_mask:0xf bank_mask:0xf
	v_pk_fma_f32 v[88:89], v[226:227], v[212:213], v[88:89] op_sel:[0,1,0]
	v_add_f32_dpp v230, v230, v230 row_half_mirror row_mask:0xf bank_mask:0xf
	v_pk_fma_f32 v[90:91], v[226:227], v[214:215], v[90:91] op_sel_hi:[1,0,1]
	v_add_f32_dpp v231, v231, v231 row_half_mirror row_mask:0xf bank_mask:0xf
	v_pk_fma_f32 v[92:93], v[226:227], v[214:215], v[92:93] op_sel:[0,1,0]
	v_add_f32_dpp v232, v232, v232 row_half_mirror row_mask:0xf bank_mask:0xf
	v_pk_fma_f32 v[94:95], v[226:227], v[216:217], v[94:95] op_sel_hi:[1,0,1]
	v_add_f32_dpp v233, v233, v233 row_half_mirror row_mask:0xf bank_mask:0xf
	v_pk_fma_f32 v[96:97], v[226:227], v[216:217], v[96:97] op_sel:[0,1,0]
	ds_read_b128 v[54:57], v240 offset:18432
	ds_read_b128 v[58:61], v240 offset:18448
	ds_read_b128 v[62:65], v241 offset:2048
	ds_read_b128 v[66:69], v241 offset:2064
	ds_read_b64 v[78:79], v242 offset:2048
	s_waitcnt lgkmcnt(10)
	v_pk_fma_f32 v[234:235], v[230:231], v[228:229], v[232:233] op_sel_hi:[1,0,1] neg_lo:[1,0,0] neg_hi:[1,0,0]
	v_pk_fma_f32 v[170:171], v[230:231], v[218:219], v[82:83] op_sel_hi:[1,0,1] neg_lo:[1,0,0] neg_hi:[1,0,0]
	v_pk_fma_f32 v[172:173], v[230:231], v[218:219], v[84:85] op_sel:[0,1,0] neg_lo:[1,0,0] neg_hi:[1,0,0]
	v_pk_fma_f32 v[174:175], v[230:231], v[220:221], v[86:87] op_sel_hi:[1,0,1] neg_lo:[1,0,0] neg_hi:[1,0,0]
	v_pk_fma_f32 v[176:177], v[230:231], v[220:221], v[88:89] op_sel:[0,1,0] neg_lo:[1,0,0] neg_hi:[1,0,0]
	v_pk_fma_f32 v[178:179], v[230:231], v[222:223], v[90:91] op_sel_hi:[1,0,1] neg_lo:[1,0,0] neg_hi:[1,0,0]
	v_pk_fma_f32 v[180:181], v[230:231], v[222:223], v[92:93] op_sel:[0,1,0] neg_lo:[1,0,0] neg_hi:[1,0,0]
	v_pk_fma_f32 v[182:183], v[230:231], v[224:225], v[94:95] op_sel_hi:[1,0,1] neg_lo:[1,0,0] neg_hi:[1,0,0]
	v_pk_fma_f32 v[184:185], v[230:231], v[224:225], v[96:97] op_sel:[0,1,0] neg_lo:[1,0,0] neg_hi:[1,0,0]
	v_pk_fma_f32 v[234:235], v[226:227], v[228:229], v[234:235] op_sel:[0,1,0]
	ds_read_b128 v[70:73], v240 offset:51200
	ds_read_b128 v[74:77], v240 offset:51216
	ds_read_b64 v[80:81], v243 offset:64
	s_mov_b64 exec, s[60:61]
	ds_write_b64 v242, v[234:235] offset:18176
	s_mov_b64 exec, -1
	v_add_u32_e32 v240, 0x800, v240
	v_add_u32_e32 v241, 0x800, v241
	v_add_u32_e32 v242, 0x800, v242
	v_add_u32_e32 v243, 0x40, v243
	s_add_i32 s62, s62, 1
	s_cmp_lt_u32 s62, 8
	s_cbranch_scc1 .Lrw_loop
	s_setprio 0
	s_branch .LBB0_1754
